# grid barrier: the 8th-from-last arriver of each XCD starts an early L2 write-back so the last arriver's write-back is short
# speedup vs baseline: 1.0040x; 1.0040x over previous
.LBB0_63:
	s_waitcnt vmcnt(0) lgkmcnt(0)
	v_readlane_b32 s14, v254, 38
	v_readlane_b32 s15, v254, 39
	v_readlane_b32 s13, v254, 40
	v_mov_b32_e32 v0, 0x20000
	ds_read_b32 v1, v0
	ds_read_b32 v2, v0 offset:4
	s_lshl_b32 s13, s13, 8
	s_add_i32 s13, s13, 0x1400
	v_mov_b32_e32 v4, s13
	v_mov_b32_e32 v5, 1
	s_nop 3
	global_atomic_add v4, v4, v5, s[14:15] sc0
	s_waitcnt vmcnt(0) lgkmcnt(0)
	v_readfirstlane_b32 s13, v4
	v_readfirstlane_b32 s20, v1
	v_readfirstlane_b32 s16, v2
	v_mov_b32_e32 v4, 0x3400
	s_add_i32 s13, s13, 1
	s_mul_i32 s20, s20, 1
	s_mul_i32 s16, s16, 1
	s_add_i32 s22, s13, 8
	s_cmp_lg_u32 s22, s20
	s_cbranch_scc1 .Lfb0_noearly
	buffer_wbl2 sc1
.Lfb0_noearly:
	s_cmp_lg_u32 s13, s20
	s_cbranch_scc1 .Lfb0_poll
	buffer_wbl2 sc1
	s_waitcnt vmcnt(0) lgkmcnt(0)
	global_atomic_add v4, v5, s[14:15]

.LBB0_670:
	s_waitcnt vmcnt(0) lgkmcnt(0)
	v_readlane_b32 s14, v254, 38
	v_readlane_b32 s15, v254, 39
	v_readlane_b32 s13, v254, 40
	v_mov_b32_e32 v0, 0x20000
	ds_read_b32 v1, v0
	ds_read_b32 v2, v0 offset:4
	s_lshl_b32 s13, s13, 8
	s_add_i32 s13, s13, 0x1400
	v_mov_b32_e32 v4, s13
	v_mov_b32_e32 v5, 1
	s_nop 3
	global_atomic_add v4, v4, v5, s[14:15] sc0
	s_waitcnt vmcnt(0) lgkmcnt(0)
	v_readfirstlane_b32 s13, v4
	v_readfirstlane_b32 s20, v1
	v_readfirstlane_b32 s16, v2
	v_mov_b32_e32 v4, 0x3400
	s_add_i32 s13, s13, 1
	s_mul_i32 s20, s20, 2
	s_mul_i32 s16, s16, 2
	s_add_i32 s22, s13, 8
	s_cmp_lg_u32 s22, s20
	s_cbranch_scc1 .Lfb1_noearly
	buffer_wbl2 sc1

.LBB0_969:
	s_waitcnt vmcnt(0) lgkmcnt(0)
	v_readlane_b32 s14, v254, 38
	v_readlane_b32 s15, v254, 39
	v_readlane_b32 s13, v254, 40
	v_mov_b32_e32 v0, 0x20000
	ds_read_b32 v1, v0
	ds_read_b32 v2, v0 offset:4
	s_lshl_b32 s13, s13, 8
	s_add_i32 s13, s13, 0x1400
	v_mov_b32_e32 v4, s13
	v_mov_b32_e32 v5, 1
	s_nop 3
	global_atomic_add v4, v4, v5, s[14:15] sc0
	s_waitcnt vmcnt(0) lgkmcnt(0)
	v_readfirstlane_b32 s13, v4
	v_readfirstlane_b32 s20, v1
	v_readfirstlane_b32 s16, v2
	v_mov_b32_e32 v4, 0x3400
	s_add_i32 s13, s13, 1
	s_mul_i32 s20, s20, 3
	s_mul_i32 s16, s16, 3
	s_add_i32 s22, s13, 8
	s_cmp_lg_u32 s22, s20
	s_cbranch_scc1 .Lfb2_noearly
	buffer_wbl2 sc1

.LBB0_1064:
	s_waitcnt vmcnt(0) lgkmcnt(0)
	v_readlane_b32 s14, v254, 38
	v_readlane_b32 s15, v254, 39
	v_readlane_b32 s13, v254, 40
	v_mov_b32_e32 v0, 0x20000
	ds_read_b32 v1, v0
	ds_read_b32 v2, v0 offset:4
	s_lshl_b32 s13, s13, 8
	s_add_i32 s13, s13, 0x1400
	v_mov_b32_e32 v4, s13
	v_mov_b32_e32 v5, 1
	s_nop 3
	global_atomic_add v4, v4, v5, s[14:15] sc0
	s_waitcnt vmcnt(0) lgkmcnt(0)
	v_readfirstlane_b32 s13, v4
	v_readfirstlane_b32 s20, v1
	v_readfirstlane_b32 s16, v2
	v_mov_b32_e32 v4, 0x3400
	s_add_i32 s13, s13, 1
	s_mul_i32 s20, s20, 4
	s_mul_i32 s16, s16, 4
	s_add_i32 s22, s13, 8
	s_cmp_lg_u32 s22, s20
	s_cbranch_scc1 .Lfb3_noearly
	buffer_wbl2 sc1

.LBB0_1124:
	s_waitcnt vmcnt(0) lgkmcnt(0)
	v_readlane_b32 s14, v254, 38
	v_readlane_b32 s15, v254, 39
	v_readlane_b32 s13, v254, 40
	v_mov_b32_e32 v0, 0x20000
	ds_read_b32 v1, v0
	ds_read_b32 v2, v0 offset:4
	s_lshl_b32 s13, s13, 8
	s_add_i32 s13, s13, 0x1400
	v_mov_b32_e32 v4, s13
	v_mov_b32_e32 v5, 1
	s_nop 3
	global_atomic_add v4, v4, v5, s[14:15] sc0
	s_waitcnt vmcnt(0) lgkmcnt(0)
	v_readfirstlane_b32 s13, v4
	v_readfirstlane_b32 s20, v1
	v_readfirstlane_b32 s16, v2
	v_mov_b32_e32 v4, 0x3400
	s_add_i32 s13, s13, 1
	s_mul_i32 s20, s20, 5
	s_mul_i32 s16, s16, 5
	s_add_i32 s22, s13, 8
	s_cmp_lg_u32 s22, s20
	s_cbranch_scc1 .Lfb4_noearly
	buffer_wbl2 sc1

.LBB0_1202:
	s_waitcnt vmcnt(0) lgkmcnt(0)
	v_readlane_b32 s14, v254, 38
	v_readlane_b32 s15, v254, 39
	v_readlane_b32 s13, v254, 40
	v_mov_b32_e32 v0, 0x20000
	ds_read_b32 v1, v0
	ds_read_b32 v2, v0 offset:4
	s_lshl_b32 s13, s13, 8
	s_add_i32 s13, s13, 0x1400
	v_mov_b32_e32 v4, s13
	v_mov_b32_e32 v5, 1
	s_nop 3
	global_atomic_add v4, v4, v5, s[14:15] sc0
	s_waitcnt vmcnt(0) lgkmcnt(0)
	v_readfirstlane_b32 s13, v4
	v_readfirstlane_b32 s20, v1
	v_readfirstlane_b32 s16, v2
	v_mov_b32_e32 v4, 0x3400
	s_add_i32 s13, s13, 1
	s_mul_i32 s20, s20, 6
	s_mul_i32 s16, s16, 6
	s_add_i32 s22, s13, 8
	s_cmp_lg_u32 s22, s20
	s_cbranch_scc1 .Lfb5_noearly
	buffer_wbl2 sc1

.LBB0_1294:
	s_waitcnt vmcnt(0) lgkmcnt(0)
	v_readlane_b32 s14, v254, 38
	v_readlane_b32 s15, v254, 39
	v_readlane_b32 s13, v254, 40
	v_mov_b32_e32 v0, 0x20000
	ds_read_b32 v1, v0
	ds_read_b32 v2, v0 offset:4
	s_lshl_b32 s13, s13, 8
	s_add_i32 s13, s13, 0x1400
	v_mov_b32_e32 v4, s13
	v_mov_b32_e32 v5, 1
	s_nop 3
	global_atomic_add v4, v4, v5, s[14:15] sc0
	s_waitcnt vmcnt(0) lgkmcnt(0)
	v_readfirstlane_b32 s13, v4
	v_readfirstlane_b32 s20, v1
	v_readfirstlane_b32 s16, v2
	v_mov_b32_e32 v4, 0x3400
	s_add_i32 s13, s13, 1
	s_mul_i32 s20, s20, 7
	s_mul_i32 s16, s16, 7
	s_add_i32 s22, s13, 8
	s_cmp_lg_u32 s22, s20
	s_cbranch_scc1 .Lfb6_noearly
	buffer_wbl2 sc1
